# group-barrier fast path: last arriver (returned count completes the round) leaves without polling; on top of v65
# baseline (speedup 1.0000x reference)
; __device__ __forceinline__ unsigned xb_ld(unsigned* p)              { return __hip_atomic_load(p, __ATOMIC_RELAXED, __HIP_MEMORY_SCOPE_AGENT); }
; __device__ __forceinline__ unsigned xb_add(unsigned* p, unsigned v) { return __hip_atomic_fetch_add(p, v, __ATOMIC_RELAXED, __HIP_MEMORY_SCOPE_AGENT); }
; #define XB_SPIN(cond, bar) do { unsigned _sp = 0; while (cond) { __builtin_amdgcn_s_sleep(1); \
;     if ((++_sp & 255u) == 0u) { if (xb_ld(&(bar)[XB_TMO])) break; if (_sp > XB_SPIN_CAP) { atomicAdd(&(bar)[XB_TMO], 1u); break; } } } } while (0)
; __device__ __forceinline__ void xcd_barrier(const XcdBarrier& b) {
;     asm volatile("s_waitcnt vmcnt(0)" ::: "memory");
;     __syncthreads();
;     if (threadIdx.x == 0) {
;         unsigned* bar = b.bar;
;         __builtin_amdgcn_s_waitcnt(0);
;         unsigned nloc = b.st[0], nx = b.st[1];
;         if (nloc == 0u) { xcd_barrier_complete(bar, b.x, nloc, nx); b.st[0] = nloc; b.st[1] = nx; }
;         const unsigned old = xb_add(&bar[XB_XSUB(b.x)], 1u);
;         const unsigned gen = old / nloc;
;         if (old + 1u == (gen + 1u) * nloc) {
;             __builtin_amdgcn_fence(__ATOMIC_RELEASE, "agent");
;             asm volatile("s_waitcnt vmcnt(0)" ::: "memory");
;             const unsigned og = xb_add(&bar[XB_TOP], 1u);
;             const unsigned tg = og / nx;
;             if (og + 1u == (tg + 1u) * nx) xb_add(&bar[XB_TOPGEN], 1u);
;             else XB_SPIN(xb_ld(&bar[XB_TOPGEN]) == tg, bar);
;             __builtin_amdgcn_fence(__ATOMIC_ACQUIRE, "agent");
;             xb_add(&bar[XB_XGEN(b.x)], 1u);
;             asm volatile("s_waitcnt vmcnt(0)" ::: "memory");
;         } else {
;             XB_SPIN(xb_ld(&bar[XB_XGEN(b.x)]) == gen, bar);
;             __builtin_amdgcn_fence(__ATOMIC_ACQUIRE, "agent");
;             asm volatile("s_waitcnt vmcnt(0)" ::: "memory");
;         }
;     }
;     __syncthreads();
.Lgb_have_flag:
	s_cmp_eq_u32 s40, 1
	s_cbranch_scc0 .Lgb_orig_g1
	s_and_b32 s40, s2, 7
	s_lshl_b32 s40, s40, 7
	s_add_u32 s38, s24, 0x313800
	s_addc_u32 s39, s25, 0
	v_mov_b32_e32 v0, s40
	v_mov_b32_e32 v1, 1
	global_atomic_add v2, v0, v1, s[38:39] sc0
	s_mov_b32 s40, 0
	s_waitcnt vmcnt(0)
	buffer_inv sc1
	v_add_u32_e32 v3, 1, v2
	v_or_b32_e32 v2, 31, v2
	v_add_u32_e32 v2, 1, v2
	v_cmp_eq_u32_e32 vcc, v3, v2
	s_cbranch_vccnz .Lgb_last_g1

; __device__ __forceinline__ unsigned xb_ld(unsigned* p)              { return __hip_atomic_load(p, __ATOMIC_RELAXED, __HIP_MEMORY_SCOPE_AGENT); }
; __device__ __forceinline__ unsigned xb_add(unsigned* p, unsigned v) { return __hip_atomic_fetch_add(p, v, __ATOMIC_RELAXED, __HIP_MEMORY_SCOPE_AGENT); }
; #define XB_SPIN(cond, bar) do { unsigned _sp = 0; while (cond) { __builtin_amdgcn_s_sleep(1); \
;     if ((++_sp & 255u) == 0u) { if (xb_ld(&(bar)[XB_TMO])) break; if (_sp > XB_SPIN_CAP) { atomicAdd(&(bar)[XB_TMO], 1u); break; } } } } while (0)
; __device__ __forceinline__ void xcd_barrier(const XcdBarrier& b) {
;     asm volatile("s_waitcnt vmcnt(0)" ::: "memory");
;     __syncthreads();
;     if (threadIdx.x == 0) {
;         unsigned* bar = b.bar;
;         __builtin_amdgcn_s_waitcnt(0);
;         unsigned nloc = b.st[0], nx = b.st[1];
;         if (nloc == 0u) { xcd_barrier_complete(bar, b.x, nloc, nx); b.st[0] = nloc; b.st[1] = nx; }
;         const unsigned old = xb_add(&bar[XB_XSUB(b.x)], 1u);
;         const unsigned gen = old / nloc;
;         if (old + 1u == (gen + 1u) * nloc) {
;             __builtin_amdgcn_fence(__ATOMIC_RELEASE, "agent");
;             asm volatile("s_waitcnt vmcnt(0)" ::: "memory");
;             const unsigned og = xb_add(&bar[XB_TOP], 1u);
;             const unsigned tg = og / nx;
;             if (og + 1u == (tg + 1u) * nx) xb_add(&bar[XB_TOPGEN], 1u);
;             else XB_SPIN(xb_ld(&bar[XB_TOPGEN]) == tg, bar);
;             __builtin_amdgcn_fence(__ATOMIC_ACQUIRE, "agent");
;             xb_add(&bar[XB_XGEN(b.x)], 1u);
;             asm volatile("s_waitcnt vmcnt(0)" ::: "memory");
;         } else {
;             XB_SPIN(xb_ld(&bar[XB_XGEN(b.x)]) == gen, bar);
;             __builtin_amdgcn_fence(__ATOMIC_ACQUIRE, "agent");
;             asm volatile("s_waitcnt vmcnt(0)" ::: "memory");
;         }
;     }
;     __syncthreads();
.Lgb_last_g1:
	s_waitcnt vmcnt(0)
	s_branch .LBB0_1165

; __device__ __forceinline__ unsigned xb_ld(unsigned* p)              { return __hip_atomic_load(p, __ATOMIC_RELAXED, __HIP_MEMORY_SCOPE_AGENT); }
; __device__ __forceinline__ unsigned xb_add(unsigned* p, unsigned v) { return __hip_atomic_fetch_add(p, v, __ATOMIC_RELAXED, __HIP_MEMORY_SCOPE_AGENT); }
; #define XB_SPIN(cond, bar) do { unsigned _sp = 0; while (cond) { __builtin_amdgcn_s_sleep(1); \
;     if ((++_sp & 255u) == 0u) { if (xb_ld(&(bar)[XB_TMO])) break; if (_sp > XB_SPIN_CAP) { atomicAdd(&(bar)[XB_TMO], 1u); break; } } } } while (0)
; __device__ __forceinline__ void xcd_barrier(const XcdBarrier& b) {
;     asm volatile("s_waitcnt vmcnt(0)" ::: "memory");
;     __syncthreads();
;     if (threadIdx.x == 0) {
;         unsigned* bar = b.bar;
;         __builtin_amdgcn_s_waitcnt(0);
;         unsigned nloc = b.st[0], nx = b.st[1];
;         if (nloc == 0u) { xcd_barrier_complete(bar, b.x, nloc, nx); b.st[0] = nloc; b.st[1] = nx; }
;         const unsigned old = xb_add(&bar[XB_XSUB(b.x)], 1u);
;         const unsigned gen = old / nloc;
;         if (old + 1u == (gen + 1u) * nloc) {
;             __builtin_amdgcn_fence(__ATOMIC_RELEASE, "agent");
;             asm volatile("s_waitcnt vmcnt(0)" ::: "memory");
;             const unsigned og = xb_add(&bar[XB_TOP], 1u);
;             const unsigned tg = og / nx;
;             if (og + 1u == (tg + 1u) * nx) xb_add(&bar[XB_TOPGEN], 1u);
;             else XB_SPIN(xb_ld(&bar[XB_TOPGEN]) == tg, bar);
;             __builtin_amdgcn_fence(__ATOMIC_ACQUIRE, "agent");
;             xb_add(&bar[XB_XGEN(b.x)], 1u);
;             asm volatile("s_waitcnt vmcnt(0)" ::: "memory");
;         } else {
;             XB_SPIN(xb_ld(&bar[XB_XGEN(b.x)]) == gen, bar);
;             __builtin_amdgcn_fence(__ATOMIC_ACQUIRE, "agent");
;             asm volatile("s_waitcnt vmcnt(0)" ::: "memory");
;         }
;     }
;     __syncthreads();
.LBB0_1245:
	s_add_i32 s0, s86, 1
	s_cmp_ge_i32 s0, s27
	s_cbranch_scc1 .LBB0_1299
	s_waitcnt vmcnt(0)
	s_waitcnt lgkmcnt(0)
	s_barrier
	s_mov_b64 s[0:1], exec
	v_readlane_b32 s8, v252, 32
	v_readlane_b32 s9, v252, 33
	v_readlane_b32 s44, v252, 46
	s_and_b64 s[8:9], s[0:1], s[8:9]
	v_readlane_b32 s45, v252, 47
	s_mov_b64 exec, s[8:9]
	s_cbranch_execz .LBB0_1298
	v_mov_b32_e32 v0, 0x23fc8
	ds_read_b32 v1, v0
	s_waitcnt lgkmcnt(0)
	v_readfirstlane_b32 s40, v1
	s_cmp_eq_u32 s40, 1
	s_cbranch_scc0 .Lgb_orig_pool
	s_and_b32 s40, s2, 7
	s_lshl_b32 s40, s40, 7
	s_add_u32 s38, s24, 0x313800
	s_addc_u32 s39, s25, 0
	v_mov_b32_e32 v0, s40
	v_mov_b32_e32 v1, 1
	global_atomic_add v2, v0, v1, s[38:39] sc0
	s_mov_b32 s40, 0
	s_waitcnt vmcnt(0)
	buffer_inv sc1
	v_add_u32_e32 v3, 1, v2
	v_or_b32_e32 v2, 31, v2
	v_add_u32_e32 v2, 1, v2
	v_cmp_eq_u32_e32 vcc, v3, v2
	s_cbranch_vccnz .Lgb_last_pool

; __device__ __forceinline__ unsigned xb_ld(unsigned* p)              { return __hip_atomic_load(p, __ATOMIC_RELAXED, __HIP_MEMORY_SCOPE_AGENT); }
; __device__ __forceinline__ unsigned xb_add(unsigned* p, unsigned v) { return __hip_atomic_fetch_add(p, v, __ATOMIC_RELAXED, __HIP_MEMORY_SCOPE_AGENT); }
; #define XB_SPIN(cond, bar) do { unsigned _sp = 0; while (cond) { __builtin_amdgcn_s_sleep(1); \
;     if ((++_sp & 255u) == 0u) { if (xb_ld(&(bar)[XB_TMO])) break; if (_sp > XB_SPIN_CAP) { atomicAdd(&(bar)[XB_TMO], 1u); break; } } } } while (0)
; __device__ __forceinline__ void xcd_barrier(const XcdBarrier& b) {
;     asm volatile("s_waitcnt vmcnt(0)" ::: "memory");
;     __syncthreads();
;     if (threadIdx.x == 0) {
;         unsigned* bar = b.bar;
;         __builtin_amdgcn_s_waitcnt(0);
;         unsigned nloc = b.st[0], nx = b.st[1];
;         if (nloc == 0u) { xcd_barrier_complete(bar, b.x, nloc, nx); b.st[0] = nloc; b.st[1] = nx; }
;         const unsigned old = xb_add(&bar[XB_XSUB(b.x)], 1u);
;         const unsigned gen = old / nloc;
;         if (old + 1u == (gen + 1u) * nloc) {
;             __builtin_amdgcn_fence(__ATOMIC_RELEASE, "agent");
;             asm volatile("s_waitcnt vmcnt(0)" ::: "memory");
;             const unsigned og = xb_add(&bar[XB_TOP], 1u);
;             const unsigned tg = og / nx;
;             if (og + 1u == (tg + 1u) * nx) xb_add(&bar[XB_TOPGEN], 1u);
;             else XB_SPIN(xb_ld(&bar[XB_TOPGEN]) == tg, bar);
;             __builtin_amdgcn_fence(__ATOMIC_ACQUIRE, "agent");
;             xb_add(&bar[XB_XGEN(b.x)], 1u);
;             asm volatile("s_waitcnt vmcnt(0)" ::: "memory");
;         } else {
;             XB_SPIN(xb_ld(&bar[XB_XGEN(b.x)]) == gen, bar);
;             __builtin_amdgcn_fence(__ATOMIC_ACQUIRE, "agent");
;             asm volatile("s_waitcnt vmcnt(0)" ::: "memory");
;         }
;     }
;     __syncthreads();
.LBB0_1377:
	s_add_i32 s66, s86, 2
	s_cmp_ge_i32 s66, s27
	s_cbranch_scc1 .LBB0_1389
	s_waitcnt vmcnt(0)
	s_waitcnt lgkmcnt(0)
	s_barrier
	s_mov_b64 s[0:1], exec
	v_readlane_b32 s38, v252, 32
	v_readlane_b32 s39, v252, 33
	v_readlane_b32 s46, v252, 46
	s_and_b64 s[38:39], s[0:1], s[38:39]
	v_readlane_b32 s47, v252, 47
	s_mov_b64 exec, s[38:39]
	s_cbranch_execz .LBB0_1617
	v_mov_b32_e32 v0, 0x23fc8
	ds_read_b32 v1, v0
	s_waitcnt lgkmcnt(0)
	v_readfirstlane_b32 s40, v1
	s_cmp_eq_u32 s40, 1
	s_cbranch_scc0 .Lgb_orig_attn
	s_and_b32 s40, s2, 7
	s_lshl_b32 s40, s40, 7
	s_add_u32 s38, s24, 0x313800
	s_addc_u32 s39, s25, 0
	v_mov_b32_e32 v0, s40
	v_mov_b32_e32 v1, 1
	global_atomic_add v2, v0, v1, s[38:39] sc0
	s_mov_b32 s40, 0
	s_waitcnt vmcnt(0)
	buffer_inv sc1
	v_add_u32_e32 v3, 1, v2
	v_or_b32_e32 v2, 31, v2
	v_add_u32_e32 v2, 1, v2
	v_cmp_eq_u32_e32 vcc, v3, v2
	s_cbranch_vccnz .Lgb_last_attn

; __device__ __forceinline__ unsigned xb_ld(unsigned* p)              { return __hip_atomic_load(p, __ATOMIC_RELAXED, __HIP_MEMORY_SCOPE_AGENT); }
; __device__ __forceinline__ unsigned xb_add(unsigned* p, unsigned v) { return __hip_atomic_fetch_add(p, v, __ATOMIC_RELAXED, __HIP_MEMORY_SCOPE_AGENT); }
; #define XB_SPIN(cond, bar) do { unsigned _sp = 0; while (cond) { __builtin_amdgcn_s_sleep(1); \
;     if ((++_sp & 255u) == 0u) { if (xb_ld(&(bar)[XB_TMO])) break; if (_sp > XB_SPIN_CAP) { atomicAdd(&(bar)[XB_TMO], 1u); break; } } } } while (0)
; __device__ __forceinline__ void xcd_barrier(const XcdBarrier& b) {
;     asm volatile("s_waitcnt vmcnt(0)" ::: "memory");
;     __syncthreads();
;     if (threadIdx.x == 0) {
;         unsigned* bar = b.bar;
;         __builtin_amdgcn_s_waitcnt(0);
;         unsigned nloc = b.st[0], nx = b.st[1];
;         if (nloc == 0u) { xcd_barrier_complete(bar, b.x, nloc, nx); b.st[0] = nloc; b.st[1] = nx; }
;         const unsigned old = xb_add(&bar[XB_XSUB(b.x)], 1u);
;         const unsigned gen = old / nloc;
;         if (old + 1u == (gen + 1u) * nloc) {
;             __builtin_amdgcn_fence(__ATOMIC_RELEASE, "agent");
;             asm volatile("s_waitcnt vmcnt(0)" ::: "memory");
;             const unsigned og = xb_add(&bar[XB_TOP], 1u);
;             const unsigned tg = og / nx;
;             if (og + 1u == (tg + 1u) * nx) xb_add(&bar[XB_TOPGEN], 1u);
;             else XB_SPIN(xb_ld(&bar[XB_TOPGEN]) == tg, bar);
;             __builtin_amdgcn_fence(__ATOMIC_ACQUIRE, "agent");
;             xb_add(&bar[XB_XGEN(b.x)], 1u);
;             asm volatile("s_waitcnt vmcnt(0)" ::: "memory");
;         } else {
;             XB_SPIN(xb_ld(&bar[XB_XGEN(b.x)]) == gen, bar);
;             __builtin_amdgcn_fence(__ATOMIC_ACQUIRE, "agent");
;             asm volatile("s_waitcnt vmcnt(0)" ::: "memory");
;         }
;     }
;     __syncthreads();
.LBB0_1672:
	s_add_i32 s8, s66, 1
	s_cmp_ge_i32 s8, s27
	s_cbranch_scc1 .LBB0_1684
	s_waitcnt vmcnt(0)
	s_waitcnt lgkmcnt(0)
	s_barrier
	s_mov_b64 s[0:1], exec
	v_readlane_b32 s38, v252, 32
	v_readlane_b32 s39, v252, 33
	v_readlane_b32 s46, v252, 46
	s_and_b64 s[38:39], s[0:1], s[38:39]
	v_readlane_b32 s47, v252, 47
	s_mov_b64 exec, s[38:39]
	s_cbranch_execz .LBB0_1727
	v_mov_b32_e32 v0, 0x23fc8
	ds_read_b32 v1, v0
	s_waitcnt lgkmcnt(0)
	v_readfirstlane_b32 s40, v1
	s_cmp_eq_u32 s40, 1
	s_cbranch_scc0 .Lgb_orig_g2
	s_and_b32 s40, s2, 7
	s_lshl_b32 s40, s40, 7
	s_add_u32 s38, s24, 0x313800
	s_addc_u32 s39, s25, 0
	v_mov_b32_e32 v0, s40
	v_mov_b32_e32 v1, 1
	global_atomic_add v2, v0, v1, s[38:39] sc0
	s_mov_b32 s40, 0
	s_waitcnt vmcnt(0)
	buffer_inv sc1
	v_add_u32_e32 v3, 1, v2
	v_or_b32_e32 v2, 31, v2
	v_add_u32_e32 v2, 1, v2
	v_cmp_eq_u32_e32 vcc, v3, v2
	s_cbranch_vccnz .Lgb_last_g2

; __device__ __forceinline__ unsigned xb_ld(unsigned* p)              { return __hip_atomic_load(p, __ATOMIC_RELAXED, __HIP_MEMORY_SCOPE_AGENT); }
; __device__ __forceinline__ unsigned xb_add(unsigned* p, unsigned v) { return __hip_atomic_fetch_add(p, v, __ATOMIC_RELAXED, __HIP_MEMORY_SCOPE_AGENT); }
; #define XB_SPIN(cond, bar) do { unsigned _sp = 0; while (cond) { __builtin_amdgcn_s_sleep(1); \
;     if ((++_sp & 255u) == 0u) { if (xb_ld(&(bar)[XB_TMO])) break; if (_sp > XB_SPIN_CAP) { atomicAdd(&(bar)[XB_TMO], 1u); break; } } } } while (0)
; __device__ __forceinline__ void xcd_barrier(const XcdBarrier& b) {
;     asm volatile("s_waitcnt vmcnt(0)" ::: "memory");
;     __syncthreads();
;     if (threadIdx.x == 0) {
;         unsigned* bar = b.bar;
;         __builtin_amdgcn_s_waitcnt(0);
;         unsigned nloc = b.st[0], nx = b.st[1];
;         if (nloc == 0u) { xcd_barrier_complete(bar, b.x, nloc, nx); b.st[0] = nloc; b.st[1] = nx; }
;         const unsigned old = xb_add(&bar[XB_XSUB(b.x)], 1u);
;         const unsigned gen = old / nloc;
;         if (old + 1u == (gen + 1u) * nloc) {
;             __builtin_amdgcn_fence(__ATOMIC_RELEASE, "agent");
;             asm volatile("s_waitcnt vmcnt(0)" ::: "memory");
;             const unsigned og = xb_add(&bar[XB_TOP], 1u);
;             const unsigned tg = og / nx;
;             if (og + 1u == (tg + 1u) * nx) xb_add(&bar[XB_TOPGEN], 1u);
;             else XB_SPIN(xb_ld(&bar[XB_TOPGEN]) == tg, bar);
;             __builtin_amdgcn_fence(__ATOMIC_ACQUIRE, "agent");
;             xb_add(&bar[XB_XGEN(b.x)], 1u);
;             asm volatile("s_waitcnt vmcnt(0)" ::: "memory");
;         } else {
;             XB_SPIN(xb_ld(&bar[XB_XGEN(b.x)]) == gen, bar);
;             __builtin_amdgcn_fence(__ATOMIC_ACQUIRE, "agent");
;             asm volatile("s_waitcnt vmcnt(0)" ::: "memory");
;         }
;     }
;     __syncthreads();
.LBB0_1775:
	s_add_i32 s8, s66, 2
	s_cmp_ge_i32 s8, s27
	s_cbranch_scc1 .LBB0_1829
	s_waitcnt vmcnt(0)
	s_waitcnt vmcnt(0) lgkmcnt(0)
	s_barrier
	s_mov_b64 s[0:1], exec
	v_readlane_b32 s38, v252, 32
	v_readlane_b32 s39, v252, 33
	s_and_b64 s[38:39], s[0:1], s[38:39]
	s_mov_b64 exec, s[38:39]
	s_cbranch_execz .LBB0_1828
	v_mov_b32_e32 v0, 0x23fc8
	ds_read_b32 v1, v0
	s_waitcnt lgkmcnt(0)
	v_readfirstlane_b32 s40, v1
	s_cmp_eq_u32 s40, 1
	s_cbranch_scc0 .Lgb_orig_g3
	s_and_b32 s40, s2, 7
	s_lshl_b32 s40, s40, 7
	s_add_u32 s38, s24, 0x313800
	s_addc_u32 s39, s25, 0
	v_mov_b32_e32 v0, s40
	v_mov_b32_e32 v1, 1
	global_atomic_add v2, v0, v1, s[38:39] sc0
	s_mov_b32 s40, 0
	s_waitcnt vmcnt(0)
	buffer_inv sc1
	v_add_u32_e32 v3, 1, v2
	v_or_b32_e32 v2, 31, v2
	v_add_u32_e32 v2, 1, v2
	v_cmp_eq_u32_e32 vcc, v3, v2
	s_cbranch_vccnz .Lgb_last_g3

; __device__ __forceinline__ unsigned xb_ld(unsigned* p)              { return __hip_atomic_load(p, __ATOMIC_RELAXED, __HIP_MEMORY_SCOPE_AGENT); }
; __device__ __forceinline__ unsigned xb_add(unsigned* p, unsigned v) { return __hip_atomic_fetch_add(p, v, __ATOMIC_RELAXED, __HIP_MEMORY_SCOPE_AGENT); }
; #define XB_SPIN(cond, bar) do { unsigned _sp = 0; while (cond) { __builtin_amdgcn_s_sleep(1); \
;     if ((++_sp & 255u) == 0u) { if (xb_ld(&(bar)[XB_TMO])) break; if (_sp > XB_SPIN_CAP) { atomicAdd(&(bar)[XB_TMO], 1u); break; } } } } while (0)
; __device__ __forceinline__ void xcd_barrier(const XcdBarrier& b) {
;     asm volatile("s_waitcnt vmcnt(0)" ::: "memory");
;     __syncthreads();
;     if (threadIdx.x == 0) {
;         unsigned* bar = b.bar;
;         __builtin_amdgcn_s_waitcnt(0);
;         unsigned nloc = b.st[0], nx = b.st[1];
;         if (nloc == 0u) { xcd_barrier_complete(bar, b.x, nloc, nx); b.st[0] = nloc; b.st[1] = nx; }
;         const unsigned old = xb_add(&bar[XB_XSUB(b.x)], 1u);
;         const unsigned gen = old / nloc;
;         if (old + 1u == (gen + 1u) * nloc) {
;             __builtin_amdgcn_fence(__ATOMIC_RELEASE, "agent");
;             asm volatile("s_waitcnt vmcnt(0)" ::: "memory");
;             const unsigned og = xb_add(&bar[XB_TOP], 1u);
;             const unsigned tg = og / nx;
;             if (og + 1u == (tg + 1u) * nx) xb_add(&bar[XB_TOPGEN], 1u);
;             else XB_SPIN(xb_ld(&bar[XB_TOPGEN]) == tg, bar);
;             __builtin_amdgcn_fence(__ATOMIC_ACQUIRE, "agent");
;             xb_add(&bar[XB_XGEN(b.x)], 1u);
;             asm volatile("s_waitcnt vmcnt(0)" ::: "memory");
;         } else {
;             XB_SPIN(xb_ld(&bar[XB_XGEN(b.x)]) == gen, bar);
;             __builtin_amdgcn_fence(__ATOMIC_ACQUIRE, "agent");
;             asm volatile("s_waitcnt vmcnt(0)" ::: "memory");
;         }
;     }
;     __syncthreads();
.LBB0_1868:
	s_add_i32 s0, s66, 3
	s_mov_b32 s86, s0
	s_cmp_ge_i32 s0, s27
	s_cbranch_scc1 .LBB0_1922
	s_waitcnt vmcnt(0)
	s_waitcnt vmcnt(0) lgkmcnt(0)
	s_barrier
	s_mov_b64 s[0:1], exec
	v_readlane_b32 s8, v252, 32
	v_readlane_b32 s9, v252, 33
	s_and_b64 s[8:9], s[0:1], s[8:9]
	s_mov_b64 exec, s[8:9]
	s_cbranch_execz .LBB0_1921
	s_cmp_eq_u32 s86, 20
	s_cbranch_scc1 .Lgb_orig_g4
	v_mov_b32_e32 v0, 0x23fc8
	ds_read_b32 v1, v0
	s_waitcnt lgkmcnt(0)
	v_readfirstlane_b32 s40, v1
	s_cmp_eq_u32 s40, 1
	s_cbranch_scc0 .Lgb_orig_g4
	s_and_b32 s40, s2, 7
	s_lshl_b32 s40, s40, 7
	s_add_u32 s38, s24, 0x313800
	s_addc_u32 s39, s25, 0
	v_mov_b32_e32 v0, s40
	v_mov_b32_e32 v1, 1
	global_atomic_add v2, v0, v1, s[38:39] sc0
	s_mov_b32 s40, 0
	s_waitcnt vmcnt(0)
	buffer_inv sc1
	v_add_u32_e32 v3, 1, v2
	v_or_b32_e32 v2, 31, v2
	v_add_u32_e32 v2, 1, v2
	v_cmp_eq_u32_e32 vcc, v3, v2
	s_cbranch_vccnz .Lgb_last_g4
